# DSA top-k level 1: skip the counting pass for candidates above the wave max key (count is 0)
# baseline (speedup 1.0000x reference)
;     ...
;           unsigned kp[32]; unsigned basek = 0u; const unsigned ones2 = 0x00010001u;
; #pragma unroll
;           for (int r2 = 0; r2 < 32; ++r2) { kp[r2] = (u[2 * r2] >> 17) | ((u[2 * r2 + 1] >> 1) & 0x7fff0000u);
;               asm("v_dot2_u32_u16 %0, %1, %2, %0" : "+v"(basek) : "v"(kp[r2]), "v"(ones2)); }
;           const int nblk = (nreg + 7) >> 3;
;           unsigned T15 = 0u; bool exact = false; int cntT = n;
;     ...
;               const unsigned c = T15 | (1u << bit), cpk = (c - 1u) * 0x00010001u; unsigned acc = 0u;
; #pragma unroll
;               for (int rb = 0; rb < 8; ++rb) { if (rb < nblk) {
; #pragma unroll
;                   for (int r2 = rb * 4; r2 < rb * 4 + 4; ++r2) { unsigned d; asm("v_pk_sub_u16 %0, %1, %2" : "=v"(d) : "v"(cpk), "v"(kp[r2]));
;                       asm("v_dot2_u32_u16 %0, %1, %2, %0" : "+v"(acc) : "v"(d), "v"(ones2)); } } }
;               const unsigned cl = (acc - (unsigned)(8 * nblk) * (c - 1u) + basek) >> 16;
;               int cnt = 0;
; #pragma unroll
;               for (int b_ = 0; b_ < 7; ++b_) cnt += __builtin_popcountll(__ballot((cl >> b_) & 1u)) << b_;
;               if (cnt >= 256) { T15 = c; cntT = cnt; }
;               if (cnt == 256) { exact = true; break; }
;           }
.LBB0_452:
	s_add_i32 s0, s61, 64
	s_add_i32 s62, s61, 1
	s_ashr_i32 s63, s0, 6
	s_cmpk_lt_i32 s61, 0x100
	s_cbranch_scc1 .LBB0_469
	s_mov_b32 s0, 0x7fff0000
	v_lshrrev_b32_e32 v71, 17, v8
	v_lshrrev_b32_e32 v72, 1, v7
	v_and_or_b32 v71, v72, s0, v71
	v_lshrrev_b32_e32 v72, 17, v10
	v_lshrrev_b32_e32 v73, 1, v9
	v_and_or_b32 v72, v73, s0, v72
	v_lshrrev_b32_e32 v73, 17, v12
	v_lshrrev_b32_e32 v74, 1, v11
	v_and_or_b32 v73, v74, s0, v73
	v_lshrrev_b32_e32 v74, 17, v14
	v_lshrrev_b32_e32 v75, 1, v13
	v_and_or_b32 v74, v75, s0, v74
	v_lshrrev_b32_e32 v75, 17, v16
	v_lshrrev_b32_e32 v76, 1, v15
	v_and_or_b32 v75, v76, s0, v75
	v_lshrrev_b32_e32 v76, 17, v18
	v_lshrrev_b32_e32 v77, 1, v17
	v_and_or_b32 v76, v77, s0, v76
	v_lshrrev_b32_e32 v77, 17, v20
	v_lshrrev_b32_e32 v78, 1, v19
	v_and_or_b32 v77, v78, s0, v77
	v_lshrrev_b32_e32 v78, 17, v22
	v_lshrrev_b32_e32 v79, 1, v21
	v_lshrrev_b32_e32 v69, 17, v6
	v_lshrrev_b32_e32 v70, 1, v5
	v_and_or_b32 v78, v79, s0, v78
	v_lshrrev_b32_e32 v79, 17, v24
	v_lshrrev_b32_e32 v80, 1, v23
	v_and_or_b32 v69, v70, s0, v69
	v_mov_b32_e32 v70, v1
	v_and_or_b32 v79, v80, s0, v79
	v_lshrrev_b32_e32 v80, 17, v26
	v_lshrrev_b32_e32 v81, 1, v25
	v_dot2_u32_u16 v70, v69, v200, v70
	v_and_or_b32 v80, v81, s0, v80
	v_lshrrev_b32_e32 v81, 17, v28
	v_lshrrev_b32_e32 v82, 1, v27
	v_dot2_u32_u16 v70, v71, v200, v70
	v_and_or_b32 v81, v82, s0, v81
	v_lshrrev_b32_e32 v82, 17, v30
	v_lshrrev_b32_e32 v83, 1, v29
	v_dot2_u32_u16 v70, v72, v200, v70
	v_and_or_b32 v82, v83, s0, v82
	v_lshrrev_b32_e32 v83, 17, v32
	v_lshrrev_b32_e32 v84, 1, v31
	v_dot2_u32_u16 v70, v73, v200, v70
	v_and_or_b32 v83, v84, s0, v83
	v_lshrrev_b32_e32 v84, 17, v34
	v_lshrrev_b32_e32 v85, 1, v33
	v_dot2_u32_u16 v70, v74, v200, v70
	v_and_or_b32 v84, v85, s0, v84
	v_lshrrev_b32_e32 v85, 17, v36
	v_lshrrev_b32_e32 v86, 1, v35
	v_dot2_u32_u16 v70, v75, v200, v70
	v_and_or_b32 v85, v86, s0, v85
	v_lshrrev_b32_e32 v86, 17, v38
	v_lshrrev_b32_e32 v87, 1, v37
	v_dot2_u32_u16 v70, v76, v200, v70
	v_and_or_b32 v86, v87, s0, v86
	v_lshrrev_b32_e32 v87, 17, v40
	v_lshrrev_b32_e32 v88, 1, v39
	v_dot2_u32_u16 v70, v77, v200, v70
	v_and_or_b32 v87, v88, s0, v87
	v_lshrrev_b32_e32 v88, 17, v42
	v_lshrrev_b32_e32 v89, 1, v41
	v_dot2_u32_u16 v70, v78, v200, v70
	v_and_or_b32 v88, v89, s0, v88
	v_lshrrev_b32_e32 v89, 17, v44
	v_lshrrev_b32_e32 v90, 1, v43
	v_dot2_u32_u16 v70, v79, v200, v70
	v_and_or_b32 v89, v90, s0, v89
	v_lshrrev_b32_e32 v90, 17, v46
	v_lshrrev_b32_e32 v91, 1, v45
	v_dot2_u32_u16 v70, v80, v200, v70
	v_and_or_b32 v90, v91, s0, v90
	v_lshrrev_b32_e32 v91, 17, v48
	v_lshrrev_b32_e32 v92, 1, v47
	v_dot2_u32_u16 v70, v81, v200, v70
	v_and_or_b32 v91, v92, s0, v91
	v_lshrrev_b32_e32 v92, 17, v50
	v_lshrrev_b32_e32 v93, 1, v49
	v_dot2_u32_u16 v70, v82, v200, v70
	v_and_or_b32 v92, v93, s0, v92
	v_lshrrev_b32_e32 v93, 17, v52
	v_lshrrev_b32_e32 v94, 1, v51
	v_dot2_u32_u16 v70, v83, v200, v70
	v_and_or_b32 v93, v94, s0, v93
	v_lshrrev_b32_e32 v94, 17, v54
	v_lshrrev_b32_e32 v95, 1, v53
	v_dot2_u32_u16 v70, v84, v200, v70
	v_and_or_b32 v94, v95, s0, v94
	v_lshrrev_b32_e32 v95, 17, v56
	v_lshrrev_b32_e32 v96, 1, v55
	v_dot2_u32_u16 v70, v85, v200, v70
	v_and_or_b32 v95, v96, s0, v95
	v_lshrrev_b32_e32 v96, 17, v58
	v_lshrrev_b32_e32 v97, 1, v57
	v_dot2_u32_u16 v70, v86, v200, v70
	v_and_or_b32 v96, v97, s0, v96
	v_lshrrev_b32_e32 v97, 17, v60
	v_lshrrev_b32_e32 v98, 1, v59
	v_dot2_u32_u16 v70, v87, v200, v70
	v_and_or_b32 v97, v98, s0, v97
	v_lshrrev_b32_e32 v98, 17, v62
	v_lshrrev_b32_e32 v99, 1, v61
	v_dot2_u32_u16 v70, v88, v200, v70
	v_and_or_b32 v98, v99, s0, v98
	v_lshrrev_b32_e32 v99, 17, v64
	v_lshrrev_b32_e32 v100, 1, v63
	v_dot2_u32_u16 v70, v89, v200, v70
	v_and_or_b32 v99, v100, s0, v99
	v_lshrrev_b32_e32 v100, 17, v66
	v_lshrrev_b32_e32 v101, 1, v65
	v_dot2_u32_u16 v70, v90, v200, v70
	v_and_or_b32 v100, v101, s0, v100
	v_lshrrev_b32_e32 v101, 17, v68
	v_lshrrev_b32_e32 v102, 1, v67
	v_dot2_u32_u16 v70, v91, v200, v70
	v_and_or_b32 v101, v102, s0, v101
	s_add_i32 s0, s63, 7
	v_dot2_u32_u16 v70, v92, v200, v70
	s_and_b32 s65, s0, 0xfffff8
	v_dot2_u32_u16 v70, v93, v200, v70
	s_cmp_gt_u32 s63, 8
	v_dot2_u32_u16 v70, v94, v200, v70
	s_cselect_b64 s[0:1], -1, 0
	s_cmp_gt_u32 s63, 16
	v_dot2_u32_u16 v70, v95, v200, v70
	s_cselect_b64 s[20:21], -1, 0
	s_cmp_gt_u32 s63, 24
	v_dot2_u32_u16 v70, v96, v200, v70
	s_cselect_b64 s[22:23], -1, 0
	s_cmp_gt_u32 s63, 32
	v_dot2_u32_u16 v70, v97, v200, v70
	s_cselect_b64 s[24:25], -1, 0
	s_cmp_gt_u32 s63, 40
	v_dot2_u32_u16 v70, v98, v200, v70
	s_cselect_b64 s[26:27], -1, 0
	s_cmp_gt_u32 s63, 48
	v_writelane_b32 v250, s52, 32
	v_dot2_u32_u16 v70, v99, v200, v70
	s_cselect_b64 s[28:29], -1, 0
	s_cmp_gt_u32 s63, 56
	v_writelane_b32 v250, s53, 33
	s_mov_b64 s[52:53], s[50:51]
	s_mov_b64 s[50:51], s[48:49]
	s_mov_b64 s[48:49], s[46:47]
	s_mov_b64 s[46:47], s[42:43]
	s_mov_b64 s[42:43], s[40:41]
	s_mov_b64 s[40:41], s[38:39]
	s_mov_b64 s[38:39], s[82:83]
	s_mov_b64 s[34:35], s[76:77]
	s_mov_b32 s82, s37
	v_dot2_u32_u16 v70, v100, v200, v70
	s_cselect_b64 s[44:45], -1, 0
	v_mov_b32_e32 v103, 14
	v_mov_b32_e32 v102, 0
	s_mov_b32 s37, s62
	v_dot2_u32_u16 v70, v101, v200, v70
	v_pk_max_u16 v117, v69, v71
	v_pk_max_u16 v119, v72, v73
	v_pk_max_u16 v117, v117, v74
	v_pk_max_u16 v119, v119, v75
	v_pk_max_u16 v117, v117, v76
	v_pk_max_u16 v119, v119, v77
	v_pk_max_u16 v117, v117, v78
	v_pk_max_u16 v119, v119, v79
	v_pk_max_u16 v117, v117, v80
	v_pk_max_u16 v119, v119, v81
	v_pk_max_u16 v117, v117, v82
	v_pk_max_u16 v119, v119, v83
	v_pk_max_u16 v117, v117, v84
	v_pk_max_u16 v119, v119, v85
	v_pk_max_u16 v117, v117, v86
	v_pk_max_u16 v119, v119, v87
	v_pk_max_u16 v117, v117, v88
	v_pk_max_u16 v119, v119, v89
	v_pk_max_u16 v117, v117, v90
	v_pk_max_u16 v119, v119, v91
	v_pk_max_u16 v117, v117, v92
	v_pk_max_u16 v119, v119, v93
	v_pk_max_u16 v117, v117, v94
	v_pk_max_u16 v119, v119, v95
	v_pk_max_u16 v117, v117, v96
	v_pk_max_u16 v119, v119, v97
	v_pk_max_u16 v117, v117, v98
	v_pk_max_u16 v119, v119, v99
	v_pk_max_u16 v117, v117, v100
	v_pk_max_u16 v119, v119, v101
	v_pk_max_u16 v117, v117, v119
	v_lshrrev_b32_e32 v119, 16, v117
	v_and_b32_e32 v117, 0xffff, v117
	v_max_u32_e32 v117, v117, v119
	s_nop 1
	v_max_u32_dpp v117, v117, v117 row_shr:1 row_mask:0xf bank_mask:0xf bound_ctrl:0
	s_nop 1
	v_max_u32_dpp v117, v117, v117 row_shr:2 row_mask:0xf bank_mask:0xf bound_ctrl:0
	s_nop 1
	v_max_u32_dpp v117, v117, v117 row_shr:4 row_mask:0xf bank_mask:0xf bound_ctrl:0
	s_nop 1
	v_max_u32_dpp v117, v117, v117 row_shr:8 row_mask:0xf bank_mask:0xf bound_ctrl:0
	s_nop 1
	v_max_u32_dpp v117, v117, v117 row_bcast:15 row_mask:0xa bank_mask:0xf
	s_nop 1
	v_max_u32_dpp v117, v117, v117 row_bcast:31 row_mask:0xc bank_mask:0xf
	s_nop 0
	v_readlane_b32 s66, v117, 63
	s_nop 3
	v_mov_b32_e32 v117, s66
	s_branch .LBB0_455
.Ll1_skip:
	s_mov_b32 s66, 0
	s_branch .Ll1_tail

;     ...
;               const unsigned c = T15 | (1u << bit), cpk = (c - 1u) * 0x00010001u; unsigned acc = 0u;
; #pragma unroll
;               for (int rb = 0; rb < 8; ++rb) { if (rb < nblk) {
; #pragma unroll
;                   for (int r2 = rb * 4; r2 < rb * 4 + 4; ++r2) { unsigned d; asm("v_pk_sub_u16 %0, %1, %2" : "=v"(d) : "v"(cpk), "v"(kp[r2]));
;                       asm("v_dot2_u32_u16 %0, %1, %2, %0" : "+v"(acc) : "v"(d), "v"(ones2)); } } }
;               const unsigned cl = (acc - (unsigned)(8 * nblk) * (c - 1u) + basek) >> 16;
;               int cnt = 0;
; #pragma unroll
;               for (int b_ = 0; b_ < 7; ++b_) cnt += __builtin_popcountll(__ballot((cl >> b_) & 1u)) << b_;
;               if (cnt >= 256) { T15 = c; cntT = cnt; }
;               if (cnt == 256) { exact = true; break; }
;           }
.Ll1_tail:
	s_cmpk_gt_u32 s66, 0xff
	s_cselect_b32 s37, s66, s37
	s_cselect_b64 vcc, -1, 0
	s_cmpk_lg_i32 s66, 0x100
	s_cselect_b64 s[56:57], -1, 0
	s_cmpk_eq_i32 s66, 0x100
	v_cndmask_b32_e32 v102, v102, v104, vcc
	s_cselect_b64 s[66:67], -1, 0
	v_subrev_co_u32_e32 v103, vcc, 1, v103
	s_or_b64 s[66:67], s[66:67], vcc
	s_andn2_b64 vcc, exec, s[66:67]
	s_cbranch_vccz .LBB0_470
.LBB0_455:
	v_lshlrev_b32_e64 v104, v103, 1
	v_or_b32_e32 v104, v104, v102
	v_cmp_gt_u32_e64 s[66:67], v104, v117
	s_and_b64 vcc, exec, s[66:67]
	s_cbranch_vccnz .Ll1_skip
	v_add_u32_e32 v105, -1, v104
	s_mov_b32 s56, 0x10001
	v_mov_b32_e32 v106, 0
	v_mul_lo_u32 v107, v105, s56
	v_pk_sub_u16 v108, v107, v69
	s_andn2_b64 vcc, exec, s[0:1]
	v_dot2_u32_u16 v106, v108, v200, v106
	v_pk_sub_u16 v108, v107, v71
	s_nop 0
	v_dot2_u32_u16 v106, v108, v200, v106
	v_pk_sub_u16 v108, v107, v72
	s_nop 0
	v_dot2_u32_u16 v106, v108, v200, v106
	v_pk_sub_u16 v108, v107, v73
	s_nop 0
	v_dot2_u32_u16 v106, v108, v200, v106
	s_cbranch_vccz .LBB0_462
	s_andn2_b64 vcc, exec, s[20:21]
	s_cbranch_vccz .LBB0_463
